# p12perm+p4perm: union/intersection of selection words by DPP row rotations + permlane swaps; cmp row-sum and LA ssq butterflies by permlane swaps (no bpermute round trips)
# speedup vs baseline: 1.0030x; 1.0030x over previous
.LBB0_440:
	s_or_b64 exec, exec, s[70:71]
	ds_read2st64_b32 v[106:107], v138 offset1:2
	s_waitcnt lgkmcnt(1)
	v_mul_f32_e32 v75, v75, v71
	v_mul_f32_e32 v63, v63, v75
	v_rcp_f32_e32 v75, v75
	s_waitcnt lgkmcnt(0)
	v_mul_f32_e32 v77, v106, v107
	v_rcp_f32_e32 v81, v77
	v_mul_f32_e32 v65, v65, v77
	v_mul_f32_e32 v65, v75, v65
	v_cvt_pk_bf16_f32 v65, v65, s0
	ds_write_b16 v140, v65 offset:18432
	v_mul_f32_e32 v65, v63, v81
	v_cvt_pk_bf16_f32 v63, v63, s0
	ds_write_b16 v140, v63 offset:36864
	v_mul_f32_e32 v63, v122, v71
	v_mul_f32_e32 v62, v62, v63
	v_rcp_f32_e32 v63, v63
	v_cvt_pk_bf16_f32 v65, v65, s0
	ds_write_b16 v140, v65
	v_mul_f32_e32 v65, v62, v81
	v_mul_f32_e32 v64, v64, v77
	v_cvt_pk_bf16_f32 v62, v62, s0
	v_mul_f32_e32 v63, v63, v64
	ds_write_b16 v141, v62 offset:37152
	v_mul_f32_e32 v62, v120, v71
	v_cvt_pk_bf16_f32 v63, v63, s0
	v_mul_f32_e32 v61, v61, v62
	v_rcp_f32_e32 v62, v62
	ds_write_b16 v141, v63 offset:18720
	v_mul_f32_e32 v63, v61, v81
	v_cvt_pk_bf16_f32 v63, v63, s0
	ds_write_b16 v141, v63 offset:576
	v_mul_f32_e32 v63, v67, v77
	v_cvt_pk_bf16_f32 v61, v61, s0
	v_mul_f32_e32 v62, v62, v63
	ds_write_b16 v141, v61 offset:37440
	v_mul_f32_e32 v61, v114, v71
	v_cvt_pk_bf16_f32 v62, v62, s0
	v_mul_f32_e32 v60, v60, v61
	v_rcp_f32_e32 v61, v61
	ds_write_b16 v141, v62 offset:19008
	v_mul_f32_e32 v62, v60, v81
	v_cvt_pk_bf16_f32 v62, v62, s0
	ds_write_b16 v141, v62 offset:864
	v_mul_f32_e32 v62, v66, v77
	v_cvt_pk_bf16_f32 v60, v60, s0
	v_mul_f32_e32 v61, v61, v62
	ds_write_b16 v141, v60 offset:37728
	v_mul_f32_e32 v60, v110, v71
	v_cvt_pk_bf16_f32 v61, v61, s0
	v_mul_f32_e32 v59, v59, v60
	v_rcp_f32_e32 v60, v60
	ds_write_b16 v141, v61 offset:19296
	v_mul_f32_e32 v61, v59, v81
	v_cvt_pk_bf16_f32 v61, v61, s0
	ds_write_b16 v141, v61 offset:1152
	v_mul_f32_e32 v61, v73, v77
	v_cvt_pk_bf16_f32 v59, v59, s0
	v_mul_f32_e32 v60, v60, v61
	ds_write_b16 v141, v59 offset:38016
	v_mul_f32_e32 v59, v104, v71
	v_cvt_pk_bf16_f32 v60, v60, s0
	v_mul_f32_e32 v58, v58, v59
	v_rcp_f32_e32 v59, v59
	ds_write_b16 v141, v60 offset:19584
	v_mul_f32_e32 v60, v58, v81
	v_cvt_pk_bf16_f32 v60, v60, s0
	ds_write_b16 v141, v60 offset:1440
	v_mul_f32_e32 v60, v72, v77
	v_cvt_pk_bf16_f32 v58, v58, s0
	v_mul_f32_e32 v59, v59, v60
	ds_write_b16 v141, v58 offset:38304
	v_mul_f32_e32 v58, v102, v71
	v_cvt_pk_bf16_f32 v59, v59, s0
	v_mul_f32_e32 v57, v57, v58
	v_rcp_f32_e32 v58, v58
	ds_write_b16 v141, v59 offset:19872
	v_mul_f32_e32 v59, v57, v81
	v_cvt_pk_bf16_f32 v59, v59, s0
	ds_write_b16 v141, v59 offset:1728
	v_mul_f32_e32 v59, v79, v77
	v_cvt_pk_bf16_f32 v57, v57, s0
	v_mul_f32_e32 v58, v58, v59
	ds_write_b16 v141, v57 offset:38592
	v_mul_f32_e32 v57, v100, v71
	v_cvt_pk_bf16_f32 v58, v58, s0
	v_mul_f32_e32 v56, v56, v57
	v_rcp_f32_e32 v57, v57
	ds_write_b16 v141, v58 offset:20160
	v_mul_f32_e32 v58, v56, v81
	v_cvt_pk_bf16_f32 v58, v58, s0
	ds_write_b16 v141, v58 offset:2016
	v_mul_f32_e32 v58, v78, v77
	v_cvt_pk_bf16_f32 v56, v56, s0
	v_mul_f32_e32 v57, v57, v58
	ds_write_b16 v141, v56 offset:38880
	v_mul_f32_e32 v56, v98, v71
	v_cvt_pk_bf16_f32 v57, v57, s0
	v_mul_f32_e32 v55, v55, v56
	v_rcp_f32_e32 v56, v56
	ds_write_b16 v141, v57 offset:20448
	v_mul_f32_e32 v57, v55, v81
	v_cvt_pk_bf16_f32 v57, v57, s0
	ds_write_b16 v141, v57 offset:2304
	v_mul_f32_e32 v57, v83, v77
	v_cvt_pk_bf16_f32 v55, v55, s0
	v_mul_f32_e32 v56, v56, v57
	ds_write_b16 v141, v55 offset:39168
	v_mul_f32_e32 v55, v96, v71
	v_cvt_pk_bf16_f32 v56, v56, s0
	v_mul_f32_e32 v54, v54, v55
	v_rcp_f32_e32 v55, v55
	ds_write_b16 v141, v56 offset:20736
	v_mul_f32_e32 v56, v54, v81
	v_cvt_pk_bf16_f32 v56, v56, s0
	ds_write_b16 v141, v56 offset:2592
	v_mul_f32_e32 v56, v82, v77
	v_cvt_pk_bf16_f32 v54, v54, s0
	v_mul_f32_e32 v55, v55, v56
	ds_write_b16 v141, v54 offset:39456
	v_mul_f32_e32 v54, v92, v71
	v_cvt_pk_bf16_f32 v55, v55, s0
	v_mul_f32_e32 v53, v53, v54
	v_rcp_f32_e32 v54, v54
	ds_write_b16 v141, v55 offset:21024
	v_mul_f32_e32 v55, v53, v81
	v_cvt_pk_bf16_f32 v55, v55, s0
	ds_write_b16 v141, v55 offset:2880
	v_mul_f32_e32 v55, v85, v77
	v_cvt_pk_bf16_f32 v53, v53, s0
	v_mul_f32_e32 v54, v54, v55
	ds_write_b16 v141, v53 offset:39744
	v_mul_f32_e32 v53, v88, v71
	v_cvt_pk_bf16_f32 v54, v54, s0
	v_mul_f32_e32 v52, v52, v53
	v_rcp_f32_e32 v53, v53
	ds_write_b16 v141, v54 offset:21312
	v_mul_f32_e32 v54, v52, v81
	v_cvt_pk_bf16_f32 v54, v54, s0
	ds_write_b16 v141, v54 offset:3168
	v_mul_f32_e32 v54, v84, v77
	v_cvt_pk_bf16_f32 v52, v52, s0
	v_mul_f32_e32 v53, v53, v54
	ds_write_b16 v141, v52 offset:40032
	v_mul_f32_e32 v52, v86, v71
	v_cvt_pk_bf16_f32 v53, v53, s0
	v_mul_f32_e32 v51, v51, v52
	v_rcp_f32_e32 v52, v52
	ds_write_b16 v141, v53 offset:21600
	v_mul_f32_e32 v53, v51, v81
	v_cvt_pk_bf16_f32 v53, v53, s0
	ds_write_b16 v141, v53 offset:3456
	v_mul_f32_e32 v53, v95, v77
	v_cvt_pk_bf16_f32 v51, v51, s0
	v_mul_f32_e32 v52, v52, v53
	ds_write_b16 v141, v51 offset:40320
	v_mul_f32_e32 v51, v80, v71
	v_cvt_pk_bf16_f32 v52, v52, s0
	v_mul_f32_e32 v50, v50, v51
	v_rcp_f32_e32 v51, v51
	ds_write_b16 v141, v52 offset:21888
	v_mul_f32_e32 v52, v50, v81
	v_cvt_pk_bf16_f32 v52, v52, s0
	ds_write_b16 v141, v52 offset:3744
	v_mul_f32_e32 v52, v94, v77
	v_cvt_pk_bf16_f32 v50, v50, s0
	v_mul_f32_e32 v51, v51, v52
	ds_write_b16 v141, v50 offset:40608
	v_mul_f32_e32 v50, v76, v71
	v_cvt_pk_bf16_f32 v51, v51, s0
	v_mul_f32_e32 v49, v49, v50
	v_rcp_f32_e32 v50, v50
	ds_write_b16 v141, v51 offset:22176
	v_mul_f32_e32 v51, v49, v81
	v_cvt_pk_bf16_f32 v51, v51, s0
	ds_write_b16 v141, v51 offset:4032
	v_mul_f32_e32 v51, v91, v77
	v_cvt_pk_bf16_f32 v49, v49, s0
	v_mul_f32_e32 v50, v50, v51
	ds_write_b16 v141, v49 offset:40896
	v_mul_f32_e32 v49, v74, v71
	v_cvt_pk_bf16_f32 v50, v50, s0
	v_mul_f32_e32 v48, v48, v49
	v_rcp_f32_e32 v49, v49
	ds_write_b16 v141, v50 offset:22464
	v_mul_f32_e32 v50, v48, v81
	v_cvt_pk_bf16_f32 v50, v50, s0
	ds_write_b16 v141, v50 offset:4320
	v_mul_f32_e32 v50, v90, v77
	v_mul_f32_e32 v49, v49, v50
	v_cvt_pk_bf16_f32 v65, v65, s0
	v_cvt_pk_bf16_f32 v49, v49, s0
	v_cvt_pk_bf16_f32 v48, v48, s0
	ds_write_b16 v141, v65 offset:288
	ds_write_b16 v141, v49 offset:22752
	ds_write_b16 v141, v48 offset:41184
	s_waitcnt lgkmcnt(0)
	s_barrier
	ds_read_b128 v[48:51], v146 offset:18432
	ds_read_b128 v[52:55], v139
	ds_read_b128 v[56:59], v139 offset:64
	ds_read_b128 v[60:63], v146 offset:18496
	ds_read_b128 v[64:67], v146 offset:23040
	ds_read_b128 v[72:75], v146 offset:23104
	s_waitcnt lgkmcnt(4)
	v_mfma_f32_16x16x32_bf16 v[48:51], v[48:51], v[52:55], 0
	ds_read_b128 v[76:79], v146 offset:27648
	ds_read_b128 v[80:83], v146 offset:27712
	ds_read_b128 v[84:87], v146 offset:32256
	ds_read_b128 v[88:91], v146 offset:32320
	s_waitcnt lgkmcnt(5)
	v_mfma_f32_16x16x32_bf16 v[64:67], v[64:67], v[52:55], 0
	v_mfma_f32_16x16x32_bf16 v[48:51], v[60:63], v[56:59], v[48:51]
	s_waitcnt lgkmcnt(4)
	v_mfma_f32_16x16x32_bf16 v[60:63], v[72:75], v[56:59], v[64:67]
	ds_read_b128 v[72:75], v146 offset:18560
	s_waitcnt lgkmcnt(4)
	v_mfma_f32_16x16x32_bf16 v[76:79], v[76:79], v[52:55], 0
	s_waitcnt lgkmcnt(2)
	v_mfma_f32_16x16x32_bf16 v[52:55], v[84:87], v[52:55], 0
	v_mfma_f32_16x16x32_bf16 v[64:67], v[80:83], v[56:59], v[76:79]
	s_waitcnt lgkmcnt(1)
	v_mfma_f32_16x16x32_bf16 v[52:55], v[88:91], v[56:59], v[52:55]
	ds_read_b128 v[56:59], v139 offset:128
	s_nop 1
	ds_read_b128 v[76:79], v139 offset:192
	ds_read_b128 v[80:83], v146 offset:18624
	s_waitcnt lgkmcnt(2)
	v_mfma_f32_16x16x32_bf16 v[48:51], v[72:75], v[56:59], v[48:51]
	ds_read_b128 v[72:75], v146 offset:23168
	ds_read_b128 v[84:87], v146 offset:23232
	s_waitcnt lgkmcnt(1)
	v_mfma_f32_16x16x32_bf16 v[60:63], v[72:75], v[56:59], v[60:63]
	ds_read_b128 v[72:75], v146 offset:27776
	ds_read_b128 v[88:91], v146 offset:27840
	s_waitcnt lgkmcnt(1)
	v_mfma_f32_16x16x32_bf16 v[64:67], v[72:75], v[56:59], v[64:67]
	ds_read_b128 v[72:75], v146 offset:32384
	ds_read_b128 v[92:95], v146 offset:32448
	v_mfma_f32_16x16x32_bf16 v[48:51], v[80:83], v[76:79], v[48:51]
	v_add_u32_e32 v83, 0xe000, v147
	s_waitcnt lgkmcnt(1)
	v_mfma_f32_16x16x32_bf16 v[52:55], v[72:75], v[56:59], v[52:55]
	v_mfma_f32_16x16x32_bf16 v[56:59], v[84:87], v[76:79], v[60:63]
	v_add_u32_e32 v85, 0xf000, v147
	v_mfma_f32_16x16x32_bf16 v[60:63], v[88:91], v[76:79], v[64:67]
	s_nop 2
	v_mov_b32_e32 v64, s57
	v_cndmask_b32_e64 v64, v48, v64, s[14:15]
	v_cndmask_b32_e64 v64, v64, v48, s[16:17]
	v_mov_b32_e32 v48, s57
	s_waitcnt lgkmcnt(0)
	v_mfma_f32_16x16x32_bf16 v[52:55], v[92:95], v[76:79], v[52:55]
	v_cndmask_b32_e64 v71, v56, v48, s[22:23]
	v_cndmask_b32_e64 v72, v57, 0, s[24:25]
	v_add_u32_e32 v77, 0xd800, v147
	v_cndmask_b32_e64 v65, 0, v49, s[16:17]
	v_cndmask_b32_e64 v66, v50, 0, s[18:19]
	v_cndmask_b32_e64 v67, v51, 0, s[20:21]
	v_cndmask_b32_e64 v73, v58, 0, s[26:27]
	v_cndmask_b32_e64 v59, v59, 0, s[28:29]
	v_cndmask_b32_e64 v80, v60, v48, s[30:31]
	ds_read2_b64 v[48:51], v77 offset1:4
	v_cvt_pk_bf16_f32 v58, v71, v72
	v_add_u32_e32 v71, 0xe800, v147
	v_cndmask_b32_e64 v81, v61, 0, s[34:35]
	v_cndmask_b32_e64 v82, v62, 0, s[36:37]
	v_cvt_pk_bf16_f32 v56, v64, v65
	v_cvt_pk_bf16_f32 v57, v66, v67
	ds_read2_b64 v[64:67], v83 offset0:64 offset1:68
	v_cvt_pk_bf16_f32 v59, v73, v59
	ds_read2_b64 v[72:75], v71 offset0:128 offset1:132
	v_cndmask_b32_e64 v84, v63, 0, s[38:39]
	ds_read2_b64 v[60:63], v85 offset0:192 offset1:196
	v_mov_b32_e32 v76, s57
	v_cndmask_b32_e64 v86, v52, v76, s[40:41]
	ds_read2_b64 v[76:79], v77 offset0:8 offset1:12
	s_waitcnt lgkmcnt(4)
	v_mfma_f32_16x16x32_bf16 v[48:51], v[48:51], v[56:59], 0
	v_cndmask_b32_e64 v87, v53, 0, s[42:43]
	v_cndmask_b32_e64 v88, v54, 0, s[44:45]
	v_cndmask_b32_e64 v89, v55, 0, s[46:47]
	s_waitcnt lgkmcnt(3)
	v_mfma_f32_16x16x32_bf16 v[64:67], v[64:67], v[56:59], 0
	s_waitcnt lgkmcnt(2)
	v_mfma_f32_16x16x32_bf16 v[72:75], v[72:75], v[56:59], 0
	s_waitcnt lgkmcnt(1)
	v_mfma_f32_16x16x32_bf16 v[52:55], v[60:63], v[56:59], 0
	ds_read2_b64 v[56:59], v83 offset0:72 offset1:76
	v_cvt_pk_bf16_f32 v60, v80, v81
	v_cvt_pk_bf16_f32 v61, v82, v84
	v_cvt_pk_bf16_f32 v62, v86, v87
	v_cvt_pk_bf16_f32 v63, v88, v89
	s_waitcnt lgkmcnt(1)
	s_nop 0
	v_mfma_f32_16x16x32_bf16 v[48:51], v[76:79], v[60:63], v[48:51]
	ds_read2_b64 v[76:79], v71 offset0:136 offset1:140
	s_waitcnt lgkmcnt(1)
	v_mfma_f32_16x16x32_bf16 v[56:59], v[56:59], v[60:63], v[64:67]
	s_nop 2
	ds_read2_b64 v[64:67], v85 offset0:200 offset1:204
	s_waitcnt lgkmcnt(1)
	v_mfma_f32_16x16x32_bf16 v[72:75], v[76:79], v[60:63], v[72:75]
	ds_read_b128 v[76:79], v148
	s_waitcnt lgkmcnt(1)
	v_mfma_f32_16x16x32_bf16 v[52:55], v[64:67], v[60:63], v[52:55]
	ds_read_b128 v[60:63], v139 offset:36864
	ds_read_b128 v[64:67], v139 offset:36928
	ds_read_b128 v[80:83], v148 offset:64
	s_waitcnt lgkmcnt(2)
	v_mfma_f32_16x16x32_bf16 v[48:51], v[76:79], v[60:63], v[48:51]
	ds_read_b128 v[76:79], v148 offset:4608
	ds_read_b128 v[84:87], v148 offset:4672
	s_waitcnt lgkmcnt(1)
	v_mfma_f32_16x16x32_bf16 v[56:59], v[76:79], v[60:63], v[56:59]
	ds_read_b128 v[76:79], v148 offset:9216
	ds_read_b128 v[88:91], v148 offset:9280
	s_waitcnt lgkmcnt(1)
	v_mfma_f32_16x16x32_bf16 v[72:75], v[76:79], v[60:63], v[72:75]
	ds_read_b128 v[76:79], v148 offset:13824
	ds_read_b128 v[92:95], v148 offset:13888
	s_waitcnt lgkmcnt(1)
	v_mfma_f32_16x16x32_bf16 v[52:55], v[76:79], v[60:63], v[52:55]
	v_mfma_f32_16x16x32_bf16 v[60:63], v[88:91], v[64:67], v[72:75]
	s_nop 2
	ds_read_b128 v[72:75], v148 offset:128
	v_mfma_f32_16x16x32_bf16 v[48:51], v[80:83], v[64:67], v[48:51]
	v_mfma_f32_16x16x32_bf16 v[56:59], v[84:87], v[64:67], v[56:59]
	s_waitcnt lgkmcnt(1)
	v_mfma_f32_16x16x32_bf16 v[52:55], v[92:95], v[64:67], v[52:55]
	ds_read_b128 v[64:67], v139 offset:36992
	ds_read_b128 v[76:79], v139 offset:37056
	ds_read_b128 v[80:83], v148 offset:192
	s_waitcnt lgkmcnt(2)
	v_mfma_f32_16x16x32_bf16 v[48:51], v[72:75], v[64:67], v[48:51]
	ds_read_b128 v[72:75], v148 offset:4736
	ds_read_b128 v[84:87], v148 offset:4800
	s_waitcnt lgkmcnt(1)
	v_mfma_f32_16x16x32_bf16 v[56:59], v[72:75], v[64:67], v[56:59]
	ds_read_b128 v[72:75], v148 offset:9344
	ds_read_b128 v[88:91], v148 offset:9408
	s_waitcnt lgkmcnt(1)
	v_mfma_f32_16x16x32_bf16 v[60:63], v[72:75], v[64:67], v[60:63]
	ds_read_b128 v[72:75], v148 offset:13952
	ds_read_b128 v[92:95], v148 offset:14016
	s_waitcnt lgkmcnt(1)
	v_mfma_f32_16x16x32_bf16 v[72:75], v[72:75], v[64:67], v[52:55]
	v_mfma_f32_16x16x32_bf16 v[64:67], v[80:83], v[76:79], v[48:51]
	v_mfma_f32_16x16x32_bf16 v[56:59], v[84:87], v[76:79], v[56:59]
	v_mfma_f32_16x16x32_bf16 v[52:55], v[88:91], v[76:79], v[60:63]
	s_nop 5
	v_mul_f32_e32 v60, v65, v65
	v_mul_f32_e32 v61, v67, v67
	v_fmac_f32_e32 v60, v64, v64
	v_fmac_f32_e32 v61, v66, v66
	v_add_f32_e32 v60, v60, v61
	v_mul_f32_e32 v61, v57, v57
	v_mul_f32_e32 v62, v59, v59
	v_fmac_f32_e32 v61, v56, v56
	v_fmac_f32_e32 v62, v58, v58
	s_waitcnt lgkmcnt(0)
	v_mfma_f32_16x16x32_bf16 v[48:51], v[92:95], v[76:79], v[72:75]
	v_add_f32_e32 v61, v61, v62
	v_add_f32_e32 v60, v60, v61
	v_mul_f32_e32 v61, v53, v53
	v_mul_f32_e32 v62, v55, v55
	v_fmac_f32_e32 v61, v52, v52
	v_fmac_f32_e32 v62, v54, v54
	v_add_f32_e32 v61, v61, v62
	v_add_f32_e32 v60, v60, v61
	v_mul_f32_e32 v61, v49, v49
	v_mul_f32_e32 v62, v51, v51
	v_fmac_f32_e32 v61, v48, v48
	v_fmac_f32_e32 v62, v50, v50
	v_add_f32_e32 v61, v61, v62
	v_and_b32_e32 v62, 64, v155
	v_add_f32_e32 v60, v60, v61
	v_xor_b32_e32 v61, 16, v155
	v_add_u32_e32 v62, 64, v62
	v_cmp_lt_i32_e32 vcc, v61, v62
	s_nop 1
	v_cndmask_b32_e32 v61, v155, v61, vcc
	v_lshlrev_b32_e32 v61, 2, v61
	v_mov_b32_e32 v61, v60
	s_nop 1
	v_permlane16_swap_b32_e32 v60, v61
	s_waitcnt lgkmcnt(0)
	v_add_f32_e32 v60, v60, v61
	v_xor_b32_e32 v61, 32, v155
	v_cmp_lt_i32_e32 vcc, v61, v62
	s_nop 1
	v_cndmask_b32_e32 v61, v155, v61, vcc
	v_lshlrev_b32_e32 v61, 2, v61
	v_mov_b32_e32 v61, v60
	s_nop 1
	v_permlane32_swap_b32_e32 v60, v61
	s_and_saveexec_b64 s[70:71], s[4:5]
	s_cbranch_execz .LBB0_429
	s_waitcnt lgkmcnt(0)
	v_add_f32_e32 v60, v60, v61
	ds_write_b32 v149, v60
	s_branch .LBB0_429

.LBB0_459:
	s_or_b64 exec, exec, s[68:69]
	ds_read2st64_b32 v[118:119], v144 offset1:4
	ds_read_b32 v123, v144 offset:1536
	s_waitcnt lgkmcnt(1)
	v_mul_f32_e32 v117, v116, v119
	v_mov_b32_e32 v122, v118
	v_mov_b32_e32 v103, v119
	v_cndmask_b32_e64 v118, v116, v117, s[12:13]
	s_waitcnt lgkmcnt(0)
	v_pk_mul_f32 v[116:117], v[122:123], v[102:103]
	v_mul_f32_e32 v102, v118, v123
	v_rcp_f32_e32 v123, v116
	v_cndmask_b32_e64 v122, v118, v102, s[14:15]
	v_mul_f32_e32 v100, v100, v122
	v_mul_f32_e32 v79, v79, v100
	v_rcp_f32_e32 v118, v100
	v_mul_f32_e32 v100, v123, v79
	v_cvt_pk_bf16_f32 v79, v79, s0
	v_cvt_pk_bf16_f32 v100, v100, s0
	ds_write_b16 v149, v79 offset:36864
	v_mul_f32_e32 v79, v121, v122
	ds_write_b16 v149, v100
	v_mul_f32_e32 v100, v78, v79
	v_rcp_f32_e32 v78, v79
	v_mul_f32_e32 v79, v123, v100
	v_pk_mul_f32 v[102:103], v[116:117], v[116:117] op_sel:[0,1] op_sel_hi:[1,0]
	v_cvt_pk_bf16_f32 v117, v79, s0
	v_mul_f32_e32 v79, v120, v122
	v_mul_f32_e32 v77, v77, v79
	v_rcp_f32_e32 v119, v79
	v_mul_f32_e32 v79, v123, v77
	v_cvt_pk_bf16_f32 v121, v77, s0
	v_mul_f32_e32 v77, v115, v122
	v_cvt_pk_bf16_f32 v120, v79, s0
	v_mul_f32_e32 v76, v76, v77
	v_rcp_f32_e32 v79, v77
	v_mul_f32_e32 v77, v123, v76
	v_cvt_pk_bf16_f32 v115, v77, s0
	v_cvt_pk_bf16_f32 v124, v76, s0
	v_pk_mul_f32 v[76:77], v[84:85], v[118:119]
	v_pk_mul_f32 v[78:79], v[86:87], v[78:79]
	v_mul_f32_e32 v84, v116, v76
	v_cvt_pk_bf16_f32 v84, v84, s0
	ds_write_b16 v149, v84 offset:18432
	ds_write_b16 v150, v117 offset:288
	v_mul_f32_e32 v84, v116, v78
	v_cvt_pk_bf16_f32 v84, v84, s0
	v_cvt_pk_bf16_f32 v100, v100, s0
	ds_write_b16 v150, v84 offset:18720
	ds_write_b16 v150, v100 offset:37152
	ds_write_b16 v150, v120 offset:576
	v_mul_f32_e32 v84, v116, v77
	v_cvt_pk_bf16_f32 v84, v84, s0
	v_pk_mul_f32 v[76:77], v[102:103], v[76:77] op_sel_hi:[0,1]
	ds_write_b16 v150, v84 offset:19008
	ds_write_b16 v150, v121 offset:37440
	v_cvt_pk_bf16_f32 v84, v76, v77
	v_mul_f32_e32 v76, v116, v79
	v_cvt_pk_bf16_f32 v76, v76, s0
	ds_write_b16 v150, v115 offset:864
	ds_write_b16 v150, v76 offset:19296
	ds_write_b16 v150, v124 offset:37728
	v_pk_mul_f32 v[76:77], v[102:103], v[78:79] op_sel_hi:[0,1]
	v_mul_f32_e32 v78, v114, v122
	v_mul_f32_e32 v75, v75, v78
	v_mul_f32_e32 v79, v123, v75
	v_cvt_pk_bf16_f32 v75, v75, s0
	v_cvt_pk_bf16_f32 v79, v79, s0
	ds_write_b16 v150, v75 offset:38016
	v_mul_f32_e32 v75, v113, v122
	v_cvt_pk_bf16_f32 v76, v76, v77
	ds_write_b16 v150, v79 offset:1152
	v_mul_f32_e32 v79, v74, v75
	v_and_b32_e32 v77, 0xffff0000, v76
	v_lshlrev_b32_e32 v76, 16, v76
	v_rcp_f32_e32 v74, v75
	v_mul_f32_e32 v75, v123, v79
	v_or_b32_sdwa v77, v77, v84 dst_sel:DWORD dst_unused:UNUSED_PAD src0_sel:DWORD src1_sel:WORD_1
	v_or_b32_sdwa v76, v76, v84 dst_sel:DWORD dst_unused:UNUSED_PAD src0_sel:DWORD src1_sel:WORD_0
	v_cvt_pk_bf16_f32 v84, v75, s0
	v_mul_f32_e32 v75, v112, v122
	v_rcp_f32_e32 v78, v78
	v_cvt_pk_bf16_f32 v85, v79, s0
	v_mul_f32_e32 v73, v73, v75
	v_rcp_f32_e32 v79, v75
	v_mul_f32_e32 v75, v123, v73
	v_cvt_pk_bf16_f32 v87, v73, s0
	v_mul_f32_e32 v73, v111, v122
	v_cvt_pk_bf16_f32 v86, v75, s0
	v_mul_f32_e32 v72, v72, v73
	v_rcp_f32_e32 v75, v73
	v_mul_f32_e32 v73, v123, v72
	v_cvt_pk_bf16_f32 v100, v73, s0
	v_cvt_pk_bf16_f32 v111, v72, s0
	v_pk_mul_f32 v[72:73], v[88:89], v[78:79]
	v_pk_mul_f32 v[74:75], v[90:91], v[74:75]
	v_mul_f32_e32 v78, v116, v72
	v_cvt_pk_bf16_f32 v78, v78, s0
	ds_write_b16 v150, v78 offset:19584
	ds_write_b16 v150, v84 offset:1440
	v_mul_f32_e32 v78, v116, v74
	v_cvt_pk_bf16_f32 v78, v78, s0
	ds_write_b16 v150, v78 offset:19872
	ds_write_b16 v150, v85 offset:38304
	ds_write_b16 v150, v86 offset:1728
	v_mul_f32_e32 v78, v116, v73
	v_cvt_pk_bf16_f32 v78, v78, s0
	v_pk_mul_f32 v[72:73], v[102:103], v[72:73] op_sel_hi:[0,1]
	ds_write_b16 v150, v78 offset:20160
	ds_write_b16 v150, v87 offset:38592
	v_cvt_pk_bf16_f32 v78, v72, v73
	v_mul_f32_e32 v72, v116, v75
	v_cvt_pk_bf16_f32 v72, v72, s0
	ds_write_b16 v150, v100 offset:2016
	ds_write_b16 v150, v72 offset:20448
	ds_write_b16 v150, v111 offset:38880
	v_pk_mul_f32 v[72:73], v[102:103], v[74:75] op_sel_hi:[0,1]
	v_cvt_pk_bf16_f32 v72, v72, v73
	v_and_b32_e32 v73, 0xffff0000, v72
	v_lshlrev_b32_e32 v72, 16, v72
	v_or_b32_sdwa v79, v73, v78 dst_sel:DWORD dst_unused:UNUSED_PAD src0_sel:DWORD src1_sel:WORD_1
	v_or_b32_sdwa v78, v72, v78 dst_sel:DWORD dst_unused:UNUSED_PAD src0_sel:DWORD src1_sel:WORD_0
	v_mul_f32_e32 v72, v110, v122
	v_mul_f32_e32 v71, v71, v72
	v_mul_f32_e32 v73, v123, v71
	v_cvt_pk_bf16_f32 v71, v71, s0
	v_cvt_pk_bf16_f32 v73, v73, s0
	ds_write_b16 v150, v71 offset:39168
	v_mul_f32_e32 v71, v109, v122
	ds_write_b16 v150, v73 offset:2304
	v_mul_f32_e32 v73, v70, v71
	v_rcp_f32_e32 v70, v71
	v_mul_f32_e32 v71, v123, v73
	v_cvt_pk_bf16_f32 v74, v71, s0
	v_mul_f32_e32 v71, v108, v122
	v_rcp_f32_e32 v72, v72
	v_cvt_pk_bf16_f32 v75, v73, s0
	v_mul_f32_e32 v69, v69, v71
	v_rcp_f32_e32 v73, v71
	v_mul_f32_e32 v71, v123, v69
	v_cvt_pk_bf16_f32 v85, v69, s0
	v_mul_f32_e32 v69, v107, v122
	v_cvt_pk_bf16_f32 v84, v71, s0
	v_mul_f32_e32 v68, v68, v69
	v_rcp_f32_e32 v71, v69
	v_mul_f32_e32 v69, v123, v68
	v_cvt_pk_bf16_f32 v86, v69, s0
	v_cvt_pk_bf16_f32 v87, v68, s0
	v_pk_mul_f32 v[68:69], v[92:93], v[72:73]
	v_pk_mul_f32 v[70:71], v[94:95], v[70:71]
	v_mul_f32_e32 v72, v116, v68
	v_cvt_pk_bf16_f32 v72, v72, s0
	ds_write_b16 v150, v72 offset:20736
	ds_write_b16 v150, v74 offset:2592
	v_mul_f32_e32 v72, v116, v70
	v_cvt_pk_bf16_f32 v72, v72, s0
	ds_write_b16 v150, v72 offset:21024
	ds_write_b16 v150, v75 offset:39456
	ds_write_b16 v150, v84 offset:2880
	v_mul_f32_e32 v72, v116, v69
	v_cvt_pk_bf16_f32 v72, v72, s0
	v_pk_mul_f32 v[68:69], v[102:103], v[68:69] op_sel_hi:[0,1]
	ds_write_b16 v150, v72 offset:21312
	ds_write_b16 v150, v85 offset:39744
	v_cvt_pk_bf16_f32 v72, v68, v69
	v_mul_f32_e32 v68, v116, v71
	v_cvt_pk_bf16_f32 v68, v68, s0
	ds_write_b16 v150, v86 offset:3168
	ds_write_b16 v150, v68 offset:21600
	ds_write_b16 v150, v87 offset:40032
	v_pk_mul_f32 v[68:69], v[102:103], v[70:71] op_sel_hi:[0,1]
	v_mul_f32_e32 v70, v106, v122
	v_mul_f32_e32 v67, v67, v70
	v_mul_f32_e32 v71, v123, v67
	v_cvt_pk_bf16_f32 v67, v67, s0
	v_cvt_pk_bf16_f32 v71, v71, s0
	ds_write_b16 v150, v67 offset:40320
	v_mul_f32_e32 v67, v105, v122
	v_cvt_pk_bf16_f32 v68, v68, v69
	ds_write_b16 v150, v71 offset:3456
	v_mul_f32_e32 v71, v66, v67
	v_and_b32_e32 v69, 0xffff0000, v68
	v_lshlrev_b32_e32 v68, 16, v68
	v_rcp_f32_e32 v66, v67
	v_mul_f32_e32 v67, v123, v71
	v_or_b32_sdwa v69, v69, v72 dst_sel:DWORD dst_unused:UNUSED_PAD src0_sel:DWORD src1_sel:WORD_1
	v_or_b32_sdwa v68, v68, v72 dst_sel:DWORD dst_unused:UNUSED_PAD src0_sel:DWORD src1_sel:WORD_0
	v_cvt_pk_bf16_f32 v72, v67, s0
	v_mul_f32_e32 v67, v104, v122
	v_rcp_f32_e32 v70, v70
	v_cvt_pk_bf16_f32 v73, v71, s0
	v_mul_f32_e32 v65, v65, v67
	v_rcp_f32_e32 v71, v67
	v_mul_f32_e32 v67, v123, v65
	v_cvt_pk_bf16_f32 v75, v65, s0
	v_mul_f32_e32 v65, v101, v122
	v_cvt_pk_bf16_f32 v74, v67, s0
	v_mul_f32_e32 v64, v64, v65
	v_rcp_f32_e32 v67, v65
	v_mul_f32_e32 v65, v123, v64
	v_cvt_pk_bf16_f32 v84, v65, s0
	v_cvt_pk_bf16_f32 v85, v64, s0
	v_pk_mul_f32 v[64:65], v[98:99], v[70:71]
	v_pk_mul_f32 v[66:67], v[96:97], v[66:67]
	v_mul_f32_e32 v70, v116, v64
	v_cvt_pk_bf16_f32 v70, v70, s0
	ds_write_b16 v150, v70 offset:21888
	ds_write_b16 v150, v72 offset:3744
	v_mul_f32_e32 v70, v116, v66
	v_cvt_pk_bf16_f32 v70, v70, s0
	ds_write_b16 v150, v70 offset:22176
	ds_write_b16 v150, v73 offset:40608
	ds_write_b16 v150, v74 offset:4032
	v_mul_f32_e32 v70, v116, v65
	v_cvt_pk_bf16_f32 v70, v70, s0
	v_pk_mul_f32 v[64:65], v[102:103], v[64:65] op_sel_hi:[0,1]
	ds_write_b16 v150, v70 offset:22464
	ds_write_b16 v150, v75 offset:40896
	v_cvt_pk_bf16_f32 v70, v64, v65
	v_mul_f32_e32 v64, v116, v67
	v_cvt_pk_bf16_f32 v64, v64, s0
	ds_write_b16 v150, v84 offset:4320
	ds_write_b16 v150, v64 offset:22752
	ds_write_b16 v150, v85 offset:41184
	v_pk_mul_f32 v[64:65], v[102:103], v[66:67] op_sel_hi:[0,1]
	v_cvt_pk_bf16_f32 v64, v64, v65
	v_and_b32_e32 v65, 0xffff0000, v64
	v_lshlrev_b32_e32 v64, 16, v64
	v_or_b32_sdwa v71, v65, v70 dst_sel:DWORD dst_unused:UNUSED_PAD src0_sel:DWORD src1_sel:WORD_1
	v_or_b32_sdwa v70, v64, v70 dst_sel:DWORD dst_unused:UNUSED_PAD src0_sel:DWORD src1_sel:WORD_0
	ds_write_b128 v157, v[76:79]
	ds_write_b128 v157, v[68:71] offset:16
	s_and_saveexec_b64 s[68:69], s[4:5]
	ds_write_b32 v145, v102
	s_or_b64 exec, exec, s[68:69]
	s_waitcnt lgkmcnt(0)
	s_barrier
	ds_read_b128 v[64:67], v159 offset:18432
	ds_read_b128 v[68:71], v146
	ds_read_b128 v[72:75], v146 offset:64
	ds_read_b128 v[76:79], v159 offset:18496
	s_waitcnt lgkmcnt(2)
	v_mfma_f32_16x16x32_bf16 v[64:67], v[64:67], v[68:71], 0
	ds_read_b128 v[84:87], v159 offset:23040
	ds_read_b128 v[88:91], v159 offset:23104
	ds_read_b128 v[92:95], v159 offset:27648
	ds_read_b128 v[96:99], v159 offset:27712
	s_waitcnt lgkmcnt(4)
	v_mfma_f32_16x16x32_bf16 v[64:67], v[76:79], v[72:75], v[64:67]
	ds_read_b128 v[76:79], v159 offset:18560
	s_waitcnt lgkmcnt(4)
	v_mfma_f32_16x16x32_bf16 v[84:87], v[84:87], v[68:71], 0
	s_waitcnt lgkmcnt(3)
	v_mfma_f32_16x16x32_bf16 v[84:87], v[88:91], v[72:75], v[84:87]
	ds_read_b128 v[88:91], v159 offset:32256
	ds_read_b128 v[100:103], v159 offset:32320
	ds_read_b128 v[104:107], v146 offset:128
	ds_read_b128 v[108:111], v159 offset:18624
	s_waitcnt lgkmcnt(6)
	v_mfma_f32_16x16x32_bf16 v[92:95], v[92:95], v[68:71], 0
	s_waitcnt lgkmcnt(1)
	v_mfma_f32_16x16x32_bf16 v[64:67], v[76:79], v[104:107], v[64:67]
	v_mfma_f32_16x16x32_bf16 v[92:95], v[96:99], v[72:75], v[92:95]
	ds_read_b128 v[96:99], v146 offset:192
	ds_read_b128 v[112:115], v159 offset:23168
	ds_read_b128 v[116:119], v159 offset:23232
	ds_read_b128 v[76:79], v159 offset:27776
	ds_read_b128 v[120:123], v159 offset:27840
	ds_read_b128 v[124:127], v159 offset:32384
	ds_read_b128 v[132:135], v159 offset:32448
	s_waitcnt lgkmcnt(6)
	v_mfma_f32_16x16x32_bf16 v[64:67], v[108:111], v[96:99], v[64:67]
	v_mov_b32_e32 v108, s81
	s_waitcnt lgkmcnt(5)
	v_mfma_f32_16x16x32_bf16 v[84:87], v[112:115], v[104:107], v[84:87]
	s_waitcnt lgkmcnt(3)
	v_mfma_f32_16x16x32_bf16 v[76:79], v[76:79], v[104:107], v[92:95]
	s_nop 2
	v_cndmask_b32_e64 v108, v64, v108, s[16:17]
	v_cndmask_b32_e64 v108, v108, v64, s[18:19]
	v_cndmask_b32_e64 v109, 0, v65, s[18:19]
	v_cndmask_b32_e64 v110, v66, 0, s[20:21]
	v_cndmask_b32_e64 v111, v67, 0, s[22:23]
	v_mfma_f32_16x16x32_bf16 v[64:67], v[116:119], v[96:99], v[84:87]
	s_waitcnt lgkmcnt(2)
	v_mfma_f32_16x16x32_bf16 v[76:79], v[120:123], v[96:99], v[76:79]
	s_nop 0
	v_mov_b32_e32 v84, s81
	s_nop 3
	v_cndmask_b32_e64 v84, v64, v84, s[24:25]
	v_mov_b32_e32 v64, s81
	v_cndmask_b32_e64 v85, v65, 0, s[26:27]
	v_cndmask_b32_e64 v92, v66, 0, s[28:29]
	v_cndmask_b32_e64 v93, v67, 0, s[30:31]
	v_cndmask_b32_e64 v112, v76, v64, s[34:35]
	v_mfma_f32_16x16x32_bf16 v[64:67], v[88:91], v[68:71], 0
	v_add_u32_e32 v69, 0xd800, v160
	v_cndmask_b32_e64 v113, v77, 0, s[36:37]
	v_cvt_pk_bf16_f32 v70, v108, v109
	v_mfma_f32_16x16x32_bf16 v[64:67], v[100:103], v[72:75], v[64:67]
	ds_read2_b64 v[74:77], v69 offset1:4
	v_add_u32_e32 v100, 0xe000, v160
	v_cvt_pk_bf16_f32 v72, v84, v85
	s_waitcnt lgkmcnt(2)
	v_mfma_f32_16x16x32_bf16 v[64:67], v[124:127], v[104:107], v[64:67]
	v_add_u32_e32 v104, 0xe800, v160
	v_add_u32_e32 v106, 0xf000, v160
	ds_read2_b64 v[84:87], v100 offset0:64 offset1:68
	s_waitcnt lgkmcnt(2)
	v_mfma_f32_16x16x32_bf16 v[64:67], v[132:135], v[96:99], v[64:67]
	v_cvt_pk_bf16_f32 v73, v92, v93
	ds_read2_b64 v[88:91], v104 offset0:128 offset1:132
	ds_read2_b64 v[92:95], v106 offset0:192 offset1:196
	ds_read2_b64 v[96:99], v69 offset0:8 offset1:12
	v_cvt_pk_bf16_f32 v71, v110, v111
	v_mov_b32_e32 v68, s81
	v_cndmask_b32_e64 v78, v78, 0, s[38:39]
	s_waitcnt lgkmcnt(4)
	v_mfma_f32_16x16x32_bf16 v[74:77], v[74:77], v[70:73], 0
	v_cndmask_b32_e64 v79, v79, 0, s[40:41]
	v_cndmask_b32_e64 v105, v64, v68, s[42:43]
	v_cndmask_b32_e64 v107, v65, 0, s[44:45]
	v_cndmask_b32_e64 v108, v66, 0, s[46:47]
	v_cndmask_b32_e64 v67, v67, 0, s[48:49]
	v_cvt_pk_bf16_f32 v64, v112, v113
	v_cvt_pk_bf16_f32 v65, v78, v79
	v_cvt_pk_bf16_f32 v66, v105, v107
	v_cvt_pk_bf16_f32 v67, v108, v67
	s_waitcnt lgkmcnt(3)
	v_mfma_f32_16x16x32_bf16 v[84:87], v[84:87], v[70:73], 0
	ds_read2_b64 v[100:103], v100 offset0:72 offset1:76
	s_waitcnt lgkmcnt(3)
	v_mfma_f32_16x16x32_bf16 v[88:91], v[88:91], v[70:73], 0
	s_waitcnt lgkmcnt(2)
	v_mfma_f32_16x16x32_bf16 v[68:71], v[92:95], v[70:73], 0
	ds_read2_b64 v[92:95], v106 offset0:200 offset1:204
	s_waitcnt lgkmcnt(2)
	v_mfma_f32_16x16x32_bf16 v[72:75], v[96:99], v[64:67], v[74:77]
	s_nop 2
	ds_read2_b64 v[76:79], v104 offset0:136 offset1:140
	s_waitcnt lgkmcnt(0)
	v_mfma_f32_16x16x32_bf16 v[76:79], v[76:79], v[64:67], v[88:91]
	s_nop 2
	ds_read_b128 v[88:91], v161
	v_mfma_f32_16x16x32_bf16 v[84:87], v[100:103], v[64:67], v[84:87]
	v_mfma_f32_16x16x32_bf16 v[64:67], v[92:95], v[64:67], v[68:71]
	s_nop 2
	ds_read_b128 v[68:71], v146 offset:36864
	ds_read_b128 v[92:95], v146 offset:36928
	ds_read_b128 v[96:99], v161 offset:64
	s_waitcnt lgkmcnt(2)
	v_mfma_f32_16x16x32_bf16 v[72:75], v[88:91], v[68:71], v[72:75]
	ds_read_b128 v[88:91], v161 offset:4608
	ds_read_b128 v[100:103], v161 offset:4672
	s_waitcnt lgkmcnt(1)
	v_mfma_f32_16x16x32_bf16 v[84:87], v[88:91], v[68:71], v[84:87]
	ds_read_b128 v[88:91], v161 offset:9216
	ds_read_b128 v[104:107], v161 offset:9280
	s_waitcnt lgkmcnt(1)
	v_mfma_f32_16x16x32_bf16 v[76:79], v[88:91], v[68:71], v[76:79]
	ds_read_b128 v[88:91], v161 offset:13824
	ds_read_b128 v[108:111], v161 offset:13888
	s_waitcnt lgkmcnt(1)
	v_mfma_f32_16x16x32_bf16 v[64:67], v[88:91], v[68:71], v[64:67]
	v_mfma_f32_16x16x32_bf16 v[68:71], v[96:99], v[92:95], v[72:75]
	v_mfma_f32_16x16x32_bf16 v[72:75], v[100:103], v[92:95], v[84:87]
	v_mfma_f32_16x16x32_bf16 v[84:87], v[104:107], v[92:95], v[76:79]
	s_nop 2
	ds_read_b128 v[76:79], v161 offset:128
	ds_read_b128 v[88:91], v146 offset:36992
	s_waitcnt lgkmcnt(2)
	v_mfma_f32_16x16x32_bf16 v[64:67], v[108:111], v[92:95], v[64:67]
	ds_read_b128 v[92:95], v161 offset:192
	ds_read_b128 v[96:99], v146 offset:37056
	ds_read_b128 v[100:103], v161 offset:4736
	ds_read_b128 v[104:107], v161 offset:4800
	ds_read_b128 v[108:111], v161 offset:9344
	ds_read_b128 v[112:115], v161 offset:9408
	s_waitcnt lgkmcnt(6)
	v_mfma_f32_16x16x32_bf16 v[68:71], v[76:79], v[88:91], v[68:71]
	s_waitcnt lgkmcnt(4)
	v_mfma_f32_16x16x32_bf16 v[76:79], v[92:95], v[96:99], v[68:71]
	ds_read_b128 v[92:95], v161 offset:13952
	ds_read_b128 v[116:119], v161 offset:14016
	s_waitcnt lgkmcnt(5)
	v_mfma_f32_16x16x32_bf16 v[68:71], v[100:103], v[88:91], v[72:75]
	s_nop 3
	v_mul_f32_e32 v120, v77, v77
	v_fmac_f32_e32 v120, v76, v76
	v_mul_f32_e32 v72, v79, v79
	v_fmac_f32_e32 v72, v78, v78
	v_add_f32_e32 v100, v120, v72
	s_waitcnt lgkmcnt(4)
	v_mfma_f32_16x16x32_bf16 v[72:75], v[104:107], v[96:99], v[68:71]
	s_waitcnt lgkmcnt(3)
	v_mfma_f32_16x16x32_bf16 v[68:71], v[108:111], v[88:91], v[84:87]
	s_waitcnt lgkmcnt(1)
	v_mfma_f32_16x16x32_bf16 v[64:67], v[92:95], v[88:91], v[64:67]
	s_nop 3
	v_mul_f32_e32 v101, v73, v73
	v_mul_f32_e32 v102, v75, v75
	v_fmac_f32_e32 v101, v72, v72
	v_mfma_f32_16x16x32_bf16 v[68:71], v[112:115], v[96:99], v[68:71]
	v_fmac_f32_e32 v102, v74, v74
	v_add_f32_e32 v84, v101, v102
	v_add_f32_e32 v84, v100, v84
	s_waitcnt lgkmcnt(0)
	v_mfma_f32_16x16x32_bf16 v[64:67], v[116:119], v[96:99], v[64:67]
	s_nop 2
	v_mul_f32_e32 v85, v69, v69
	v_mul_f32_e32 v86, v71, v71
	v_fmac_f32_e32 v85, v68, v68
	v_fmac_f32_e32 v86, v70, v70
	v_add_f32_e32 v85, v85, v86
	v_add_f32_e32 v84, v84, v85
	v_mul_f32_e32 v85, v65, v65
	v_mul_f32_e32 v86, v67, v67
	v_fmac_f32_e32 v85, v64, v64
	v_fmac_f32_e32 v86, v66, v66
	v_add_f32_e32 v85, v85, v86
	v_and_b32_e32 v86, 64, v162
	v_add_f32_e32 v84, v84, v85
	v_xor_b32_e32 v85, 16, v162
	v_add_u32_e32 v86, 64, v86
	v_cmp_lt_i32_e32 vcc, v85, v86
	s_nop 1
	v_cndmask_b32_e32 v85, v162, v85, vcc
	v_lshlrev_b32_e32 v85, 2, v85
	v_mov_b32_e32 v85, v84
	s_nop 1
	v_permlane16_swap_b32_e32 v84, v85
	s_waitcnt lgkmcnt(0)
	v_add_f32_e32 v84, v84, v85
	v_xor_b32_e32 v85, 32, v162
	v_cmp_lt_i32_e32 vcc, v85, v86
	s_nop 1
	v_cndmask_b32_e32 v85, v162, v85, vcc
	v_lshlrev_b32_e32 v85, 2, v85
	v_mov_b32_e32 v85, v84
	s_nop 1
	v_permlane32_swap_b32_e32 v84, v85
	s_and_saveexec_b64 s[68:69], s[8:9]
	s_cbranch_execz .LBB0_450
	s_waitcnt lgkmcnt(0)
	v_add_f32_e32 v84, v84, v85
	ds_write_b32 v163, v84
	s_branch .LBB0_450

.LBB0_1027:
	s_waitcnt vmcnt(0)
	v_mov_b32_e32 v0, v80
	v_mov_b32_e32 v1, v80
	s_nop 1
	v_permlane16_swap_b32_e32 v0, v1
	v_add_f32_e32 v0, v0, v1
	v_mov_b32_e32 v1, v0
	s_nop 1
	v_permlane32_swap_b32_e32 v0, v1
	v_add_f32_e32 v0, v0, v1
	v_div_scale_f32 v1, s[0:1], v0, v0, 1.0
	v_rcp_f32_e32 v2, v1
	v_div_scale_f32 v3, vcc, 1.0, v0, 1.0
	v_fma_f32 v7, -v1, v2, 1.0
	v_fmac_f32_e32 v2, v7, v2
	v_mul_f32_e32 v7, v3, v2
	v_fma_f32 v8, -v1, v7, v3
	v_fmac_f32_e32 v7, v8, v2
	v_fma_f32 v1, -v1, v7, v3
	v_div_fmas_f32 v1, v1, v2, v7
	v_div_fixup_f32 v1, v1, v0, 1.0
	v_cmp_lt_f32_e32 vcc, 0, v0
	s_nop 1
	v_cndmask_b32_e32 v135, 0, v1, vcc
	s_and_saveexec_b64 s[0:1], s[4:5]
	s_cbranch_execz .LBB0_1029
	v_lshl_add_u32 v0, s20, 6, v154
	ds_write_b32 v172, v135
	ds_write_b32 v0, v81

.Lradix_done:
	v_cmp_eq_u32_e64 s[26:27], s31, v3
	v_cmp_eq_u32_e64 s[24:25], s31, v2
	s_and_b64 s[78:79], s[20:21], s[26:27]
	v_cmp_lt_u32_e64 s[0:1], s31, v3
	v_cmp_lt_u32_e64 s[22:23], s31, v2
	v_cndmask_b32_e64 v2, 0, 1, s[78:79]
	s_and_b64 s[80:81], vcc, s[24:25]
	v_cmp_ne_u32_e64 s[26:27], 0, v2
	v_cndmask_b32_e64 v2, 0, 1, s[80:81]
	s_and_b64 s[82:83], s[20:21], s[0:1]
	v_cmp_ne_u32_e64 s[24:25], 0, v2
	v_cndmask_b32_e64 v2, 0, 1, s[82:83]
	s_and_b64 s[22:23], vcc, s[22:23]
	v_cmp_ne_u32_e64 s[0:1], 0, v2
	v_cndmask_b32_e64 v2, 0, 1, s[22:23]
	s_bcnt1_i32_b64 s31, s[0:1]
	v_cmp_ne_u32_e64 s[0:1], 0, v2
	v_and_b32_e32 v3, s26, v126
	s_bcnt1_i32_b64 s0, s[0:1]
	v_and_b32_e32 v2, s27, v125
	v_bcnt_u32_b32 v3, v3, 0
	v_and_b32_e32 v7, s24, v126
	s_add_i32 s31, s31, s0
	v_bcnt_u32_b32 v2, v2, v3
	v_and_b32_e32 v3, s25, v125
	v_bcnt_u32_b32 v7, v7, 0
	s_sub_i32 s31, 16, s31
	s_bcnt1_i32_b64 s0, s[26:27]
	v_bcnt_u32_b32 v3, v3, v7
	v_add_u32_e32 v3, s0, v3
	v_cmp_gt_i32_e64 s[0:1], s31, v2
	s_and_b64 s[0:1], s[78:79], s[0:1]
	s_or_b64 s[0:1], s[82:83], s[0:1]
	v_cndmask_b32_e64 v2, 0, 1, s[0:1]
	v_cmp_gt_i32_e64 s[0:1], s31, v3
	s_and_b64 s[0:1], s[80:81], s[0:1]
	s_or_b64 s[0:1], s[22:23], s[0:1]
	v_cmp_ne_u32_e64 s[24:25], 0, v2
	v_cndmask_b32_e64 v2, 0, 1, s[0:1]
	v_cmp_ne_u32_e64 s[0:1], 0, v2
	s_and_saveexec_b64 s[22:23], s[6:7]
	v_mov_b32_e32 v8, s24
	v_mov_b32_e32 v9, s25
	v_mov_b32_e32 v10, s0
	v_mov_b32_e32 v11, s1
	ds_write_b128 v175, v[8:11]
	s_or_b64 exec, exec, s[22:23]
	v_cmp_eq_u32_e64 s[26:27], s30, v1
	v_cmp_lt_u32_e64 s[0:1], s30, v1
	v_cmp_lt_u32_e64 s[22:23], s30, v0
	v_cmp_eq_u32_e64 s[24:25], s30, v0
	s_and_b64 s[30:31], s[20:21], s[26:27]
	v_cndmask_b32_e64 v0, 0, 1, s[30:31]
	s_and_b64 s[78:79], vcc, s[24:25]
	v_cmp_ne_u32_e64 s[26:27], 0, v0
	v_cndmask_b32_e64 v0, 0, 1, s[78:79]
	s_and_b64 s[20:21], s[20:21], s[0:1]
	v_cmp_ne_u32_e64 s[24:25], 0, v0
	v_cndmask_b32_e64 v0, 0, 1, s[20:21]
	v_cmp_ne_u32_e64 s[0:1], 0, v0
	s_bcnt1_i32_b64 s77, s[0:1]
	s_and_b64 s[0:1], vcc, s[22:23]
	v_cndmask_b32_e64 v0, 0, 1, s[0:1]
	v_cmp_ne_u32_e32 vcc, 0, v0
	v_and_b32_e32 v1, s26, v126
	s_bcnt1_i32_b64 s22, vcc
	v_and_b32_e32 v0, s27, v125
	v_bcnt_u32_b32 v1, v1, 0
	v_and_b32_e32 v2, s24, v126
	s_add_i32 s77, s77, s22
	v_bcnt_u32_b32 v0, v0, v1
	v_and_b32_e32 v1, s25, v125
	v_bcnt_u32_b32 v2, v2, 0
	s_sub_i32 s77, 16, s77
	s_bcnt1_i32_b64 s22, s[26:27]
	v_bcnt_u32_b32 v1, v1, v2
	v_add_u32_e32 v1, s22, v1
	v_cmp_gt_i32_e32 vcc, s77, v0
	s_and_b64 s[22:23], s[30:31], vcc
	v_cmp_gt_i32_e32 vcc, s77, v1
	s_or_b64 s[20:21], s[20:21], s[22:23]
	s_and_b64 s[22:23], s[78:79], vcc
	v_cndmask_b32_e64 v0, 0, 1, s[20:21]
	s_or_b64 s[0:1], s[0:1], s[22:23]
	v_cmp_ne_u32_e64 s[20:21], 0, v0
	v_cndmask_b32_e64 v0, 0, 1, s[0:1]
	v_cmp_ne_u32_e32 vcc, 0, v0
	s_and_saveexec_b64 s[0:1], s[6:7]
	v_mov_b32_e32 v0, s20
	v_mov_b32_e32 v1, s21
	v_mov_b32_e32 v2, vcc_lo
	v_mov_b32_e32 v3, vcc_hi
	ds_write_b128 v176, v[0:3]
	s_or_b64 exec, exec, s[0:1]
	s_waitcnt lgkmcnt(0)
	s_barrier
	ds_read_b32 v0, v157
	s_waitcnt lgkmcnt(0)
	v_mov_b32_e32 v1, v0
	s_nop 1
	v_or_b32_dpp v3, v0, v0 row_ror:4 row_mask:0xf bank_mask:0xf
	v_and_b32_dpp v2, v1, v1 row_ror:4 row_mask:0xf bank_mask:0xf
	s_nop 1
	v_or_b32_dpp v3, v3, v3 row_ror:8 row_mask:0xf bank_mask:0xf
	v_and_b32_dpp v2, v2, v2 row_ror:8 row_mask:0xf bank_mask:0xf
	v_mov_b32_e32 v0, v3
	v_mov_b32_e32 v1, v2
	s_nop 1
	v_permlane16_swap_b32_e32 v3, v0
	v_permlane16_swap_b32_e32 v2, v1
	v_or_b32_e32 v3, v3, v0
	v_and_b32_e32 v2, v2, v1
	v_mov_b32_e32 v0, v3
	v_mov_b32_e32 v1, v2
	s_nop 1
	v_permlane32_swap_b32_e32 v3, v0
	v_permlane32_swap_b32_e32 v2, v1
	v_or_b32_e32 v3, v3, v0
	v_and_b32_e32 v0, v2, v1
	v_readlane_b32 s20, v3, 0
	v_readlane_b32 s21, v3, 1
	v_readlane_b32 s22, v3, 2
	v_readlane_b32 s23, v3, 3
	v_readlane_b32 s26, v0, 0
	v_readlane_b32 s27, v0, 1
	v_readlane_b32 s77, v0, 2
	v_readlane_b32 s78, v0, 3
	s_and_saveexec_b64 s[0:1], s[8:9]
	s_cbranch_execz .LBB0_1038
	v_mov_b32_e32 v0, s23
	v_mov_b32_e32 v1, s22
	v_cndmask_b32_e64 v0, v0, v1, s[14:15]
	v_mov_b32_e32 v1, s21
	v_cndmask_b32_e64 v0, v0, v1, s[12:13]
	v_mov_b32_e32 v1, s20
	v_cndmask_b32_e64 v0, v0, v1, s[10:11]
	v_and_b32_e32 v1, v0, v158
	v_cmp_ne_u32_e32 vcc, 0, v1
	s_and_b64 exec, exec, vcc
	s_cbranch_execz .LBB0_1038
	s_bcnt1_i32_b32 s24, s20
	v_mov_b32_e32 v1, s24
	s_bcnt1_i32_b32 s24, s21
	v_mov_b32_e32 v2, s24
	s_bcnt1_i32_b32 s24, s22
	v_cndmask_b32_e64 v1, v1, 0, s[10:11]
	v_cndmask_b32_e64 v2, 0, v2, s[16:17]
	v_mov_b32_e32 v3, s24
	v_and_b32_e32 v0, v0, v159
	v_cndmask_b32_e64 v3, 0, v3, s[18:19]
	v_bcnt_u32_b32 v0, v0, 0
	v_lshlrev_b32_e32 v1, 2, v1
	v_lshlrev_b32_e32 v2, 2, v2
	v_add3_u32 v1, s72, v1, v2
	v_lshlrev_b32_e32 v2, 2, v3
	v_lshlrev_b32_e32 v0, 2, v0
	v_add3_u32 v0, v1, v2, v0
	ds_write_b32 v0, v129
